# experiment: grid barrier acquire invalidate issued at arrival (overlapping the wait) instead of after release
# speedup vs baseline: 1.0094x; 1.0094x over previous
; __device__ __forceinline__ unsigned xb_ld(unsigned* p)              { return __hip_atomic_load(p, __ATOMIC_RELAXED, __HIP_MEMORY_SCOPE_AGENT); }
; __device__ __forceinline__ unsigned xb_add(unsigned* p, unsigned v) { return __hip_atomic_fetch_add(p, v, __ATOMIC_RELAXED, __HIP_MEMORY_SCOPE_AGENT); }
; #define XB_SPIN(cond, bar) do { unsigned _sp = 0; while (cond) { __builtin_amdgcn_s_sleep(1); \
;     if ((++_sp & 255u) == 0u) { if (xb_ld(&(bar)[XB_TMO])) break; if (_sp > XB_SPIN_CAP) { atomicAdd(&(bar)[XB_TMO], 1u); break; } } } } while (0)
; __device__ __forceinline__ void xcd_barrier(const XcdBarrier& b) {
;     ...
;         const unsigned old = xb_add(&bar[XB_XSUB(b.x)], 1u);
;         const unsigned gen = old / nloc;
;         if (old + 1u == (gen + 1u) * nloc) {
;             __builtin_amdgcn_fence(__ATOMIC_RELEASE, "agent");
;             asm volatile("s_waitcnt vmcnt(0)" ::: "memory");
;             const unsigned og = xb_add(&bar[XB_TOP], 1u);
;             const unsigned tg = og / nx;
;             if (og + 1u == (tg + 1u) * nx) xb_add(&bar[XB_TOPGEN], 1u);
;             else XB_SPIN(xb_ld(&bar[XB_TOPGEN]) == tg, bar);
;             __builtin_amdgcn_fence(__ATOMIC_ACQUIRE, "agent");
;             xb_add(&bar[XB_XGEN(b.x)], 1u);
;             asm volatile("s_waitcnt vmcnt(0)" ::: "memory");
;         } else {
;             XB_SPIN(xb_ld(&bar[XB_XGEN(b.x)]) == gen, bar);
;             __builtin_amdgcn_fence(__ATOMIC_ACQUIRE, "agent");
;             asm volatile("s_waitcnt vmcnt(0)" ::: "memory");
.LBB0_533:
	s_or_b64 exec, exec, s[12:13]
	v_cvt_f32_u32_e32 v5, v3
	s_waitcnt vmcnt(0)
	v_readfirstlane_b32 s2, v4
	v_sub_u32_e32 v4, 0, v3
	v_rcp_iflag_f32_e32 v5, v5
	v_add_u32_e32 v6, s2, v2
	v_mul_f32_e32 v5, 0x4f7ffffe, v5
	v_cvt_u32_f32_e32 v5, v5
	v_mul_lo_u32 v2, v4, v5
	v_mul_hi_u32 v2, v5, v2
	v_add_u32_e32 v2, v5, v2
	v_mul_hi_u32 v2, v6, v2
	v_mul_lo_u32 v4, v2, v3
	v_sub_u32_e32 v4, v6, v4
	v_add_u32_e32 v5, 1, v2
	v_cmp_ge_u32_e32 vcc, v4, v3
	s_nop 1
	v_cndmask_b32_e32 v2, v2, v5, vcc
	v_sub_u32_e32 v5, v4, v3
	v_cndmask_b32_e32 v4, v4, v5, vcc
	v_add_u32_e32 v5, 1, v2
	v_cmp_ge_u32_e32 vcc, v4, v3
	v_add_u32_e32 v4, 1, v6
	s_nop 0
	v_cndmask_b32_e32 v2, v2, v5, vcc
	v_mul_lo_u32 v5, v3, v2
	v_add_u32_e32 v3, v5, v3
	v_cmp_ne_u32_e32 vcc, v4, v3
	s_and_saveexec_b64 s[10:11], vcc
	s_xor_b64 s[10:11], exec, s[10:11]
	s_cbranch_execz .LBB0_547
	s_waitcnt lgkmcnt(0)
	s_add_u32 s16, s6, 0x32c03500
	s_addc_u32 s17, s7, 0
	s_add_i32 s2, s80, -1
	v_mov_b32_e32 v2, s2
	buffer_inv sc1
	global_load_dword v0, v1, s[16:17] sc1
	s_waitcnt vmcnt(0)
	v_cmp_eq_u32_e32 vcc, v0, v2
	s_and_saveexec_b64 s[12:13], vcc
	s_cbranch_execz .LBB0_546
	s_add_u32 s14, s6, 0x32c00200
	s_addc_u32 s15, s7, 0
	s_mov_b32 s2, 1
	s_mov_b64 s[18:19], 0
	s_branch .LBB0_537

; __device__ __forceinline__ unsigned xb_add(unsigned* p, unsigned v) { return __hip_atomic_fetch_add(p, v, __ATOMIC_RELAXED, __HIP_MEMORY_SCOPE_AGENT); }
; __device__ __forceinline__ void xcd_barrier(const XcdBarrier& b) {
;     ...
;         if (old + 1u == (gen + 1u) * nloc) {
;             __builtin_amdgcn_fence(__ATOMIC_RELEASE, "agent");
;             asm volatile("s_waitcnt vmcnt(0)" ::: "memory");
;             const unsigned og = xb_add(&bar[XB_TOP], 1u);
.LBB0_547:
	s_andn2_saveexec_b64 s[10:11], s[10:11]
	s_cbranch_execz .LBB0_567
	s_mov_b64 s[10:11], exec
	buffer_wbl2 sc1
	buffer_inv sc1
	s_waitcnt lgkmcnt(0)
	s_waitcnt vmcnt(0)
	v_mbcnt_lo_u32_b32 v2, s10, 0
	v_mbcnt_hi_u32_b32 v2, s11, v2
	v_cmp_eq_u32_e32 vcc, 0, v2
	s_and_saveexec_b64 s[12:13], vcc
	s_cbranch_execz .LBB0_550
	s_bcnt1_i32_b64 s2, s[10:11]
	v_mov_b32_e32 v3, s2
	v_mov_b32_e32 v4, 0x32c03000
	global_atomic_add v3, v4, v3, s[6:7] offset:1024 sc0

; __device__ __forceinline__ unsigned xb_add(unsigned* p, unsigned v) { return __hip_atomic_fetch_add(p, v, __ATOMIC_RELAXED, __HIP_MEMORY_SCOPE_AGENT); }
; __device__ __forceinline__ void xcd_barrier(const XcdBarrier& b) {
;     ...
;             __builtin_amdgcn_fence(__ATOMIC_ACQUIRE, "agent");
;             xb_add(&bar[XB_XGEN(b.x)], 1u);
.LBB0_564:
	s_or_b64 exec, exec, s[6:7]
	s_mov_b64 s[6:7], exec
	v_mbcnt_lo_u32_b32 v0, s6, 0
	v_mbcnt_hi_u32_b32 v0, s7, v0
	v_cmp_eq_u32_e32 vcc, 0, v0
	s_and_saveexec_b64 s[10:11], vcc
	s_cbranch_execz .LBB0_566
	s_bcnt1_i32_b64 s2, s[6:7]
	v_mov_b32_e32 v0, s2
